# phase-5 compress-input build: next row's 13 loads in flight while the current row is converted and stored (second register set, counted vmcnt), on top of P7 fill batching
# baseline (speedup 1.0000x reference)
.LBB0_572:
	s_or_b64 exec, exec, s[0:1]
	s_mov_b64 s[6:7], s[92:93]
	v_mov_b32_e32 v26, v230
	s_waitcnt lgkmcnt(0)
	s_barrier
	s_load_dwordx2 s[0:1], s[6:7], 0xd8
	v_ashrrev_i32_e32 v0, 6, v26
	v_readlane_b32 s2, v252, 4
	v_and_b32_e32 v19, 63, v26
	s_nop 0
	v_add_u32_e32 v64, s2, v0
	s_movk_i32 s2, 0x4000
	v_cmp_gt_i32_e32 vcc, s2, v64
	v_ashrrev_i32_e32 v65, 31, v64
	s_and_saveexec_b64 s[12:13], vcc
	s_cbranch_execz .LBB0_581
	s_load_dwordx2 s[16:17], s[6:7], 0x10
	s_load_dwordx2 s[18:19], s[6:7], 0x60
	s_load_dwordx2 s[20:21], s[6:7], 0x78
	v_and_b32_e32 v1, 1, v26
	v_lshl_add_u32 v28, v0, 6, s56
	v_lshlrev_b32_e32 v0, 3, v0
	v_lshlrev_b32_e32 v18, 5, v1
	v_cmp_eq_u32_e32 vcc, 0, v1
	v_lshl_add_u32 v29, s87, 6, v0
	v_lshlrev_b64 v[0:1], 12, v[64:65]
	s_waitcnt lgkmcnt(0)
	s_add_u32 s14, s0, 0x186a0000
	v_lshrrev_b32_e32 v27, 1, v19
	v_lshl_or_b32 v0, v19, 6, v0
	s_addc_u32 s15, s1, 0
	v_lshlrev_b32_e32 v2, 6, v27
	v_lshl_add_u64 v[0:1], s[0:1], 0, v[0:1]
	s_mov_b64 s[4:5], 0x46a0020
	s_ashr_i32 s95, s94, 31
	s_mov_b32 s26, 0x6dc9c883
	v_mov_b32_e32 v17, 0
	s_lshl_b32 s2, s90, 9
	s_lshl_b32 s3, s90, 6
	v_lshl_add_u64 v[20:21], v[0:1], 0, s[4:5]
	s_lshl_b64 s[22:23], s[94:95], 12
	v_readlane_b32 s87, v252, 5
	s_mov_b64 s[24:25], 0
	s_movk_i32 s30, 0xff
	s_mov_b32 s31, 0xf000
	s_movk_i32 s33, 0x2600
	s_movk_i32 s34, 0x2000
	s_mov_b32 s27, 0x3fc45f30
	v_lshlrev_b32_e32 v22, 2, v2
	s_movk_i32 s35, 0x3fff
	v_mov_b32_e32 v30, 0x500
	v_mov_b32_e32 v31, 0x400
	v_lshlrev_b32_e32 v24, 1, v18
	s_mov_b32 s8, 0
	v_mov_b32_e32 v32, v64
	v_mov_b32_e32 v216, v32
	v_mov_b32_e32 v217, v28
	v_mov_b32_e32 v218, v29
	v_bfe_u32 v197, v216, 1, 8
	v_cmp_ne_u32_e64 s[38:39], s30, v197
	v_cmp_ge_i32_e64 s[40:41], s35, v216
	s_and_b64 s[38:39], s[38:39], s[40:41]
	s_and_saveexec_b64 s[40:41], s[38:39]
	s_cbranch_execz .Lp5pf_skip_a
	v_and_or_b32 v198, v218, s31, v27
	v_lshl_add_u32 v199, v197, 4, v198
	v_mov_b64_e32 v[200:201], s[14:15]
	v_mad_u64_u32 v[200:201], s[42:43], v199, s33, v[200:201]
	v_cmp_gt_u32_e64 s[42:43], s34, v216
	v_and_b32_e32 v202, 64, v217
	v_mov_b32_e32 v205, 0
	v_cndmask_b32_e64 v204, v30, v31, s[42:43]
	v_lshl_add_u64 v[200:201], v[200:201], 0, v[204:205]
	v_lshlrev_b32_e32 v204, 1, v202
	v_lshl_add_u64 v[200:201], v[200:201], 0, v[204:205]
	v_mov_b32_e32 v204, v24
	v_lshl_add_u64 v[200:201], v[200:201], 0, v[204:205]
	global_load_dwordx4 v[112:115], v[200:201], off offset:48
	global_load_dwordx4 v[116:119], v[200:201], off offset:32
	global_load_dwordx4 v[120:123], v[200:201], off offset:16
	global_load_dwordx4 v[124:127], v[200:201], off
	v_mov_b32_e32 v206, s21
	v_mov_b32_e32 v207, s19
	v_cndmask_b32_e64 v209, v206, v207, s[42:43]
	v_mov_b32_e32 v206, s20
	v_mov_b32_e32 v207, s18
	v_cndmask_b32_e64 v208, v206, v207, s[42:43]
	v_mov_b32_e32 v204, v22
	v_lshl_add_u64 v[208:209], v[208:209], 0, v[204:205]
	v_lshlrev_b32_e32 v204, 2, v18
	v_lshl_add_u64 v[208:209], v[208:209], 0, v[204:205]
	global_load_dwordx4 v[164:167], v[208:209], off
	global_load_dwordx4 v[168:171], v[208:209], off offset:16
	global_load_dwordx4 v[172:175], v[208:209], off offset:32
	global_load_dwordx4 v[176:179], v[208:209], off offset:48
	global_load_dwordx4 v[180:183], v[208:209], off offset:64
	global_load_dwordx4 v[184:187], v[208:209], off offset:80
	global_load_dwordx4 v[188:191], v[208:209], off offset:96
	global_load_dwordx4 v[192:195], v[208:209], off offset:112
	s_and_b64 s[44:45], vcc, s[42:43]
	s_and_b64 exec, exec, s[44:45]
	s_cbranch_execz .Lp5pf_skip_a
	v_lshlrev_b32_e32 v204, 2, v199
	global_load_dword v196, v204, s[16:17]
.Lp5pf_skip_a:
	s_mov_b64 exec, s[40:41]
	s_waitcnt vmcnt(0)
	s_branch .LBB0_575

.LBB0_575:
	s_waitcnt vmcnt(4)
	v_mov_b64_e32 v[0:1], v[112:113]
	v_mov_b64_e32 v[2:3], v[114:115]
	v_mov_b64_e32 v[4:5], v[116:117]
	v_mov_b64_e32 v[6:7], v[118:119]
	v_mov_b64_e32 v[8:9], v[120:121]
	v_mov_b64_e32 v[10:11], v[122:123]
	v_mov_b64_e32 v[12:13], v[124:125]
	v_mov_b64_e32 v[14:15], v[126:127]
	v_mov_b64_e32 v[80:81], v[164:165]
	v_mov_b64_e32 v[82:83], v[166:167]
	v_mov_b64_e32 v[84:85], v[168:169]
	v_mov_b64_e32 v[86:87], v[170:171]
	v_mov_b64_e32 v[88:89], v[172:173]
	v_mov_b64_e32 v[90:91], v[174:175]
	v_mov_b64_e32 v[92:93], v[176:177]
	v_mov_b64_e32 v[94:95], v[178:179]
	v_mov_b64_e32 v[96:97], v[180:181]
	v_mov_b64_e32 v[98:99], v[182:183]
	v_mov_b64_e32 v[100:101], v[184:185]
	v_mov_b64_e32 v[102:103], v[186:187]
	v_mov_b64_e32 v[104:105], v[188:189]
	v_mov_b64_e32 v[106:107], v[190:191]
	v_mov_b64_e32 v[108:109], v[192:193]
	v_mov_b64_e32 v[110:111], v[194:195]
	v_mov_b32_e32 v16, v196
	v_add_u32_e32 v216, s94, v32
	v_add_u32_e32 v217, s2, v28
	v_add_u32_e32 v218, s3, v29
	v_bfe_u32 v197, v216, 1, 8
	v_cmp_ne_u32_e64 s[38:39], s30, v197
	v_cmp_ge_i32_e64 s[40:41], s35, v216
	s_and_b64 s[38:39], s[38:39], s[40:41]
	s_and_saveexec_b64 s[40:41], s[38:39]
	s_cbranch_execz .Lp5pf_skip_b
	v_and_or_b32 v198, v218, s31, v27
	v_lshl_add_u32 v199, v197, 4, v198
	v_mov_b64_e32 v[200:201], s[14:15]
	v_mad_u64_u32 v[200:201], s[42:43], v199, s33, v[200:201]
	v_cmp_gt_u32_e64 s[42:43], s34, v216
	v_and_b32_e32 v202, 64, v217
	v_mov_b32_e32 v205, 0
	v_cndmask_b32_e64 v204, v30, v31, s[42:43]
	v_lshl_add_u64 v[200:201], v[200:201], 0, v[204:205]
	v_lshlrev_b32_e32 v204, 1, v202
	v_lshl_add_u64 v[200:201], v[200:201], 0, v[204:205]
	v_mov_b32_e32 v204, v24
	v_lshl_add_u64 v[200:201], v[200:201], 0, v[204:205]
	global_load_dwordx4 v[112:115], v[200:201], off offset:48
	global_load_dwordx4 v[116:119], v[200:201], off offset:32
	global_load_dwordx4 v[120:123], v[200:201], off offset:16
	global_load_dwordx4 v[124:127], v[200:201], off
	v_mov_b32_e32 v206, s21
	v_mov_b32_e32 v207, s19
	v_cndmask_b32_e64 v209, v206, v207, s[42:43]
	v_mov_b32_e32 v206, s20
	v_mov_b32_e32 v207, s18
	v_cndmask_b32_e64 v208, v206, v207, s[42:43]
	v_mov_b32_e32 v204, v22
	v_lshl_add_u64 v[208:209], v[208:209], 0, v[204:205]
	v_lshlrev_b32_e32 v204, 2, v18
	v_lshl_add_u64 v[208:209], v[208:209], 0, v[204:205]
	global_load_dwordx4 v[164:167], v[208:209], off
	global_load_dwordx4 v[168:171], v[208:209], off offset:16
	global_load_dwordx4 v[172:175], v[208:209], off offset:32
	global_load_dwordx4 v[176:179], v[208:209], off offset:48
	global_load_dwordx4 v[180:183], v[208:209], off offset:64
	global_load_dwordx4 v[184:187], v[208:209], off offset:80
	global_load_dwordx4 v[188:191], v[208:209], off offset:96
	global_load_dwordx4 v[192:195], v[208:209], off offset:112
	s_and_b64 s[44:45], vcc, s[42:43]
	s_and_b64 exec, exec, s[44:45]
	s_cbranch_execz .Lp5pf_skip_b
	v_lshlrev_b32_e32 v204, 2, v199
	global_load_dword v196, v204, s[16:17]
.Lp5pf_skip_b:
	s_mov_b64 exec, s[40:41]
	v_bfe_u32 v33, v32, 1, 8
	v_cmp_ne_u32_e64 s[4:5], s30, v33
	s_and_saveexec_b64 s[10:11], s[4:5]
	s_xor_b64 s[10:11], exec, s[10:11]
	s_cbranch_execz .LBB0_579
	v_cmp_gt_u32_e64 s[4:5], s34, v32
	s_and_b64 s[36:37], vcc, s[4:5]
	s_and_saveexec_b64 s[28:29], s[36:37]
	s_cbranch_execz .LBB0_578
	v_lshlrev_b32_e32 v34, 16, v12
	v_and_b32_e32 v35, 0xffff0000, v12
	v_lshlrev_b32_e32 v36, 16, v8
	v_and_b32_e32 v37, 0xffff0000, v8
	v_lshlrev_b32_e32 v12, 16, v13
	v_and_b32_e32 v13, 0xffff0000, v13
	v_lshlrev_b32_e32 v8, 16, v9
	v_and_b32_e32 v9, 0xffff0000, v9
	v_lshlrev_b32_e32 v38, 16, v14
	v_and_b32_e32 v39, 0xffff0000, v14
	v_lshlrev_b32_e32 v40, 16, v10
	v_and_b32_e32 v41, 0xffff0000, v10
	v_lshlrev_b32_e32 v14, 16, v15
	v_and_b32_e32 v15, 0xffff0000, v15
	v_lshlrev_b32_e32 v10, 16, v11
	v_and_b32_e32 v11, 0xffff0000, v11
	v_cvt_f32_i32_e32 v16, v16
	v_cvt_f64_f32_e32 v[42:43], v16
	v_mul_f32_e32 v23, 0x3e4693b0, v16
	v_mul_f32_e32 v25, 0x3d1a08c8, v16
	v_mul_f32_e32 v33, 0x3beef74e, v16
	v_mul_f32_e32 v52, 0x3ab95d22, v16
	v_mul_f32_e32 v54, 0x398fc8f7, v16
	v_mul_f32_e32 v56, 0x385f10c4, v16
	v_mul_f32_e32 v16, 0x372d07a7, v16
	v_mul_f64 v[44:45], v[42:43], s[26:27]
	v_cvt_f64_f32_e32 v[46:47], v23
	v_cvt_f64_f32_e32 v[48:49], v25
	v_cvt_f64_f32_e32 v[50:51], v33
	v_cvt_f64_f32_e32 v[52:53], v52
	v_cvt_f64_f32_e32 v[54:55], v54
	v_cvt_f64_f32_e32 v[56:57], v56
	v_cvt_f64_f32_e32 v[58:59], v16
	v_rndne_f64_e32 v[44:45], v[44:45]
	v_mul_f64 v[60:61], v[46:47], s[26:27]
	v_mul_f64 v[62:63], v[48:49], s[26:27]
	v_mul_f64 v[66:67], v[50:51], s[26:27]
	v_mul_f64 v[68:69], v[52:53], s[26:27]
	v_mul_f64 v[70:71], v[54:55], s[26:27]
	v_mul_f64 v[72:73], v[56:57], s[26:27]
	v_mul_f64 v[74:75], v[58:59], s[26:27]
	v_fma_f64 v[42:43], v[42:43], s[26:27], -v[44:45]
	v_rndne_f64_e32 v[44:45], v[60:61]
	v_rndne_f64_e32 v[60:61], v[62:63]
	v_rndne_f64_e32 v[62:63], v[66:67]
	v_rndne_f64_e32 v[66:67], v[68:69]
	v_rndne_f64_e32 v[68:69], v[70:71]
	v_rndne_f64_e32 v[70:71], v[72:73]
	v_rndne_f64_e32 v[72:73], v[74:75]
	v_cvt_f32_f64_e32 v16, v[42:43]
	v_fma_f64 v[42:43], v[46:47], s[26:27], -v[44:45]
	v_fma_f64 v[44:45], v[48:49], s[26:27], -v[60:61]
	v_fma_f64 v[46:47], v[50:51], s[26:27], -v[62:63]
	v_fma_f64 v[48:49], v[52:53], s[26:27], -v[66:67]
	v_fma_f64 v[50:51], v[54:55], s[26:27], -v[68:69]
	v_fma_f64 v[52:53], v[56:57], s[26:27], -v[70:71]
	v_fma_f64 v[54:55], v[58:59], s[26:27], -v[72:73]
	v_sin_f32_e32 v56, v16
	v_cos_f32_e32 v58, v16
	v_cvt_f32_f64_e32 v16, v[42:43]
	v_cvt_f32_f64_e32 v23, v[44:45]
	v_cvt_f32_f64_e32 v25, v[46:47]
	v_cvt_f32_f64_e32 v33, v[48:49]
	v_cvt_f32_f64_e32 v49, v[50:51]
	v_cvt_f32_f64_e32 v51, v[52:53]
	v_cvt_f32_f64_e32 v53, v[54:55]
	v_sin_f32_e32 v57, v16
	v_sin_f32_e32 v42, v23
	v_sin_f32_e32 v43, v25
	v_sin_f32_e32 v46, v33
	v_sin_f32_e32 v47, v49
	v_sin_f32_e32 v50, v51
	v_cos_f32_e32 v52, v51
	v_sin_f32_e32 v51, v53
	v_cos_f32_e32 v59, v16
	v_cos_f32_e32 v44, v23
	v_cos_f32_e32 v45, v25
	v_cos_f32_e32 v48, v33
	v_cos_f32_e32 v49, v49
	v_cos_f32_e32 v53, v53
	v_pk_mul_f32 v[54:55], v[56:57], v[34:35]
	v_pk_mul_f32 v[56:57], v[56:57], v[36:37]
	v_pk_mul_f32 v[60:61], v[42:43], v[12:13]
	v_pk_mul_f32 v[42:43], v[42:43], v[8:9]
	v_pk_mul_f32 v[62:63], v[46:47], v[38:39]
	v_pk_mul_f32 v[46:47], v[46:47], v[40:41]
	v_pk_mul_f32 v[66:67], v[50:51], v[14:15]
	v_pk_mul_f32 v[50:51], v[50:51], v[10:11]
	v_pk_fma_f32 v[36:37], v[58:59], v[36:37], v[54:55]
	v_pk_fma_f32 v[34:35], v[58:59], v[34:35], v[56:57] neg_lo:[0,0,1] neg_hi:[0,0,1]
	v_pk_fma_f32 v[54:55], v[44:45], v[8:9], v[60:61]
	v_pk_fma_f32 v[8:9], v[44:45], v[12:13], v[42:43] neg_lo:[0,0,1] neg_hi:[0,0,1]
	v_pk_fma_f32 v[40:41], v[48:49], v[40:41], v[62:63]
	v_pk_fma_f32 v[38:39], v[48:49], v[38:39], v[46:47] neg_lo:[0,0,1] neg_hi:[0,0,1]
	v_pk_fma_f32 v[42:43], v[52:53], v[10:11], v[66:67]
	v_pk_fma_f32 v[10:11], v[52:53], v[14:15], v[50:51] neg_lo:[0,0,1] neg_hi:[0,0,1]
	v_cvt_pk_bf16_f32 v12, v34, v35
	v_cvt_pk_bf16_f32 v13, v8, v9
	v_cvt_pk_bf16_f32 v14, v38, v39
	v_cvt_pk_bf16_f32 v15, v10, v11
	v_cvt_pk_bf16_f32 v8, v36, v37
	v_cvt_pk_bf16_f32 v9, v54, v55
	v_cvt_pk_bf16_f32 v10, v40, v41
	v_cvt_pk_bf16_f32 v11, v42, v43
.LBB0_578:
	s_or_b64 exec, exec, s[28:29]
	v_lshlrev_b32_e32 v44, 16, v12
	v_and_b32_e32 v45, 0xffff0000, v12
	v_lshlrev_b32_e32 v12, 16, v13
	v_and_b32_e32 v13, 0xffff0000, v13
	v_lshlrev_b32_e32 v46, 16, v14
	v_and_b32_e32 v47, 0xffff0000, v14
	v_lshlrev_b32_e32 v14, 16, v15
	v_and_b32_e32 v15, 0xffff0000, v15
	v_pk_add_f32 v[80:81], v[80:81], v[44:45]
	v_pk_add_f32 v[82:83], v[82:83], v[12:13]
	v_pk_add_f32 v[84:85], v[84:85], v[46:47]
	v_pk_add_f32 v[86:87], v[86:87], v[14:15]
	v_cvt_pk_bf16_f32 v12, v80, v81
	v_cvt_pk_bf16_f32 v13, v82, v83
	v_cvt_pk_bf16_f32 v14, v84, v85
	v_cvt_pk_bf16_f32 v15, v86, v87
	global_store_dwordx4 v[20:21], v[12:15], off offset:-32
	v_lshlrev_b32_e32 v44, 16, v8
	v_and_b32_e32 v45, 0xffff0000, v8
	v_lshlrev_b32_e32 v8, 16, v9
	v_and_b32_e32 v9, 0xffff0000, v9
	v_lshlrev_b32_e32 v46, 16, v10
	v_and_b32_e32 v47, 0xffff0000, v10
	v_lshlrev_b32_e32 v10, 16, v11
	v_and_b32_e32 v11, 0xffff0000, v11
	v_pk_add_f32 v[88:89], v[88:89], v[44:45]
	v_pk_add_f32 v[90:91], v[90:91], v[8:9]
	v_pk_add_f32 v[92:93], v[92:93], v[46:47]
	v_pk_add_f32 v[94:95], v[94:95], v[10:11]
	v_cvt_pk_bf16_f32 v8, v88, v89
	v_cvt_pk_bf16_f32 v9, v90, v91
	v_cvt_pk_bf16_f32 v10, v92, v93
	v_cvt_pk_bf16_f32 v11, v94, v95
	global_store_dwordx4 v[20:21], v[8:11], off offset:-16
	v_lshlrev_b32_e32 v44, 16, v4
	v_and_b32_e32 v45, 0xffff0000, v4
	v_lshlrev_b32_e32 v4, 16, v5
	v_and_b32_e32 v5, 0xffff0000, v5
	v_lshlrev_b32_e32 v46, 16, v6
	v_and_b32_e32 v47, 0xffff0000, v6
	v_lshlrev_b32_e32 v6, 16, v7
	v_and_b32_e32 v7, 0xffff0000, v7
	v_pk_add_f32 v[96:97], v[96:97], v[44:45]
	v_pk_add_f32 v[98:99], v[98:99], v[4:5]
	v_pk_add_f32 v[100:101], v[100:101], v[46:47]
	v_pk_add_f32 v[102:103], v[102:103], v[6:7]
	v_cvt_pk_bf16_f32 v4, v96, v97
	v_cvt_pk_bf16_f32 v5, v98, v99
	v_cvt_pk_bf16_f32 v6, v100, v101
	v_cvt_pk_bf16_f32 v7, v102, v103
	global_store_dwordx4 v[20:21], v[4:7], off
	v_lshlrev_b32_e32 v44, 16, v0
	v_and_b32_e32 v45, 0xffff0000, v0
	v_lshlrev_b32_e32 v0, 16, v1
	v_and_b32_e32 v1, 0xffff0000, v1
	v_lshlrev_b32_e32 v46, 16, v2
	v_and_b32_e32 v47, 0xffff0000, v2
	v_lshlrev_b32_e32 v2, 16, v3
	v_and_b32_e32 v3, 0xffff0000, v3
	v_pk_add_f32 v[104:105], v[104:105], v[44:45]
	v_pk_add_f32 v[106:107], v[106:107], v[0:1]
	v_pk_add_f32 v[108:109], v[108:109], v[46:47]
	v_pk_add_f32 v[110:111], v[110:111], v[2:3]
	v_cvt_pk_bf16_f32 v0, v104, v105
	v_cvt_pk_bf16_f32 v1, v106, v107
	v_cvt_pk_bf16_f32 v2, v108, v109
	v_cvt_pk_bf16_f32 v3, v110, v111
